# down GEMM tile order: each XCD round takes 4 token panels x 8 column tiles (was 8 x 4), so every 4 MB U panel streams from memory once instead of once per round
# speedup vs baseline: 1.0141x; 1.0074x over previous
; #define PG8_STAGE(bufoff, gbase, voff) do { _Pragma("unroll") for (int _i = 0; _i < 2; ++_i) \
;         __builtin_amdgcn_global_load_lds((const unsigned*)((const char*)(gbase) + (voff)[_i]), (PG8_LAS unsigned*)(lds + (bufoff) + ldsw + _i * 8192), 16, 0, 0); } while (0)
; #define PG8_WAIT_V(n) asm volatile("s_waitcnt vmcnt(" #n ")" ::: "memory")
; #define PG8_BAR __builtin_amdgcn_s_barrier()
; template <class Epi, class Sched, bool ALIGN_EPI = false, bool SP2 = false>
; __device__ __forceinline__ void gemm_phase(PG8_LAS unsigned char* lds, const Gemm g, const Sched& S, const Epi& E) {
;     ...
;     const int tid = tid_, wid = __builtin_amdgcn_readfirstlane(tid >> 6), lane = tid & 63, wr = wid >> 2, wc = wid & 3, fr = lane & 15, fq = lane >> 4;
;     const int K = g.K, nt = K / BK;
;     unsigned voffA[2], voffB[2];
; #pragma unroll
;     for (int i = 0; i < 2; ++i) { int R, C; stage_rc(tid * 16 + i * 8192, R, C); const int Rb = Epi::PERM ? ((R & ~31) + perm32(R & 31)) : R;
;         voffA[i] = (unsigned)(R * K + C) * 2u; voffB[i] = (unsigned)(Rb * K + C) * 2u; }
;     const size_t kstep = (size_t)(BK * 2);
;     const size_t hstep = (size_t)HALF * K * 2;
;     const size_t tstep = 2 * hstep;
;     const unsigned ldsw = (unsigned)wid * 1024u;
;     const int aoff = lds_byte(wr * 64 + fr, fq * 8), boff = lds_byte(wc * 32 + fr, fq * 8);
;     ...
;     const char* cA = (const char*)g.A + (size_t)cur.pm * tstep; const char* cB = (const char*)g.Bt + (size_t)cur.pn * tstep;
;     S.a_ready(cur);
;     if constexpr (SP2) {
;         PG8_STAGE(PG8_SB(0, 0), cB, voffB); PG8_STAGE(PG8_SB(0, 1), cB + hstep, voffB); PG8_STAGE(PG8_SA(0, 0), cA, voffA); PG8_STAGE(PG8_SA(0, 1), cA + hstep, voffA);
;         if (wr == 1) PG8_BAR;
;         PG8_WAIT_V(2); PG8_BAR;
;         PG8_STAGE(PG8_SB(1, 0), cB + kstep, voffB); PG8_STAGE(PG8_SB(1, 1), cB + hstep + kstep, voffB);
;         PG8_WAIT_V(4); PG8_BAR;
.LBB0_687:
.LBB0_688:
	s_cmp_le_i32 s86, s22
	s_cselect_b64 s[4:5], -1, 0
	s_and_b64 s[6:7], s[4:5], s[6:7]
	s_andn2_b64 vcc, exec, s[6:7]
	s_cbranch_vccnz .LBB0_709
	s_mov_b64 s[6:7], 0
	v_mov_b32_e32 v10, v230
	s_and_b64 vcc, exec, s[40:41]
	v_readfirstlane_b32 s10, v10
	s_cbranch_vccnz .LBB0_709
	v_lshlrev_b32_e32 v0, 4, v10
	v_add_u32_e32 v1, 0x2000, v0
	v_ashrrev_i32_e32 v2, 31, v1
	v_lshrrev_b32_e32 v2, 22, v2
	v_add_u32_e32 v2, v1, v2
	v_ashrrev_i32_e32 v4, 10, v2
	v_mul_i32_i24_e32 v2, 0x400, v4
	v_sub_u32_e32 v1, v1, v2
	v_lshrrev_b32_e32 v2, 4, v1
	s_add_u32 s8, s50, s6
	v_bitop3_b32 v1, v2, v1, 32 bitop3:0x6c
	s_addc_u32 s9, s51, s7
	v_ashrrev_i32_e32 v2, 31, v1
	s_add_u32 s20, s8, 0x25000000
	v_lshrrev_b32_e32 v2, 26, v2
	s_addc_u32 s21, s9, 0
	s_mul_i32 s6, s74, 0x6000000
	v_add_u32_e32 v2, v1, v2
	s_waitcnt lgkmcnt(0)
	v_lshlrev_b32_e32 v3, 3, v4
	s_add_u32 s6, s8, s6
	v_ashrrev_i32_e32 v5, 6, v2
	v_and_b32_e32 v3, -16, v3
	s_addc_u32 s7, s9, 0
	v_add_u32_e32 v3, v5, v3
	s_add_u32 s23, s6, 0x5000000
	v_and_b32_e32 v6, 3, v5
	s_mov_b32 s6, 0x3ffe0
	v_lshrrev_b32_e32 v7, 2, v3
	v_lshlrev_b32_e32 v8, 1, v3
	v_and_b32_e32 v2, 0xc0, v2
	v_and_or_b32 v6, v3, s6, v6
	v_and_b32_e32 v7, 4, v7
	v_and_b32_e32 v8, 24, v8
	v_sub_u32_e32 v1, v1, v2
	v_or3_b32 v7, v6, v7, v8
	v_lshlrev_b32_e32 v6, 5, v4
	v_ashrrev_i16_sdwa v1, v224, sext(v1) dst_sel:DWORD dst_unused:UNUSED_PAD src0_sel:DWORD src1_sel:BYTE_0
	v_and_b32_e32 v8, 32, v6
	v_bfe_i32 v6, v1, 0, 16
	v_add_lshl_u32 v1, v8, v6, 1
	v_lshl_add_u32 v128, v7, 14, v1
	v_lshl_add_u32 v130, v3, 14, v1
	v_bfe_i32 v1, v10, 27, 1
	v_lshrrev_b32_e32 v1, 22, v1
	v_add_u32_e32 v1, v0, v1
	v_and_b32_e32 v1, 0xfffffc00, v1
	v_sub_u32_e32 v0, v0, v1
	v_lshrrev_b32_e32 v1, 4, v0
	v_ashrrev_i32_e32 v2, 31, v10
	v_bitop3_b32 v0, v1, v0, 32 bitop3:0x6c
	v_lshrrev_b32_e32 v2, 26, v2
	v_ashrrev_i32_e32 v1, 31, v0
	v_add_u32_e32 v2, v10, v2
	v_lshrrev_b32_e32 v1, 26, v1
	v_ashrrev_i32_e32 v8, 6, v2
	v_add_u32_e32 v1, v0, v1
	v_lshlrev_b32_e32 v2, 3, v8
	v_ashrrev_i32_e32 v7, 6, v1
	v_and_b32_e32 v2, -16, v2
	v_add_u32_e32 v2, v7, v2
	v_and_b32_e32 v3, 3, v7
	v_lshrrev_b32_e32 v9, 2, v2
	v_lshlrev_b32_e32 v11, 1, v2
	v_and_b32_e32 v1, 0xc0, v1
	s_addc_u32 s34, s7, 0
	s_ashr_i32 s11, s10, 6
	v_and_or_b32 v3, v2, s6, v3
	v_and_b32_e32 v9, 4, v9
	v_and_b32_e32 v11, 24, v11
	v_sub_u32_e32 v0, v0, v1
	s_ashr_i32 s40, s10, 8
	s_lshl_b32 s35, s11, 10
	v_or3_b32 v3, v3, v9, v11
	v_lshlrev_b32_e32 v9, 5, v8
	v_ashrrev_i16_sdwa v0, v224, sext(v0) dst_sel:DWORD dst_unused:UNUSED_PAD src0_sel:DWORD src1_sel:BYTE_0
	v_readlane_b32 s6, v255, 14
	v_and_b32_e32 v11, 32, v9
	v_bfe_i32 v9, v0, 0, 16
	v_readlane_b32 s7, v255, 15
	v_readlane_b32 s32, v255, 20
	s_nop 3
	s_bfe_u32 s33, s32, 0x10002
	s_lshl_b32 s6, s6, 1
	s_lshl_b32 s33, s33, 22
	s_add_u32 s6, s6, s33
	s_ashr_i32 s33, s48, 31
	s_add_u32 s44, s23, s6
	v_add_lshl_u32 v0, v11, v9, 1
	s_addc_u32 s45, s34, s7
	s_add_i32 s36, s35, 0
	v_lshl_add_u32 v204, v3, 14, v0
	s_add_i32 m0, s36, 0x10000
	v_lshl_add_u32 v132, v2, 14, v0
	global_load_lds_dwordx4 v204, s[44:45]
	s_add_i32 m0, s36, 0x12000
	s_add_u32 s6, s44, 0x200000
	global_load_lds_dwordx4 v128, s[44:45]
	s_addc_u32 s7, s45, 0
	s_add_i32 m0, s36, 0x14000
	v_mov_b32_e32 v129, v205
	global_load_lds_dwordx4 v204, s[6:7]
	s_add_i32 m0, s36, 0x16000
	v_lshl_add_u64 v[0:1], s[44:45], 0, v[204:205]
	global_load_lds_dwordx4 v128, s[6:7]
	v_readlane_b32 s6, v255, 22
	v_readlane_b32 s7, v255, 23
	s_nop 3
	s_bitset0_b32 s6, 24
	s_add_u32 s16, s20, s6
	s_addc_u32 s17, s21, s7
	s_add_i32 s37, s36, 0x2000
	s_mov_b32 m0, s36
	s_add_u32 s6, s16, 0x200000
	global_load_lds_dwordx4 v132, s[16:17]
	s_mov_b32 m0, s37
	s_addc_u32 s7, s17, 0
	s_add_i32 s57, s36, 0x4000
	global_load_lds_dwordx4 v130, s[16:17]
	s_mov_b32 m0, s57
	s_add_i32 s75, s36, 0x6000
	global_load_lds_dwordx4 v132, s[6:7]
	s_mov_b32 m0, s75
	s_cmp_eq_u32 s40, 1
	global_load_lds_dwordx4 v130, s[6:7]
	s_cselect_b64 s[6:7], -1, 0
	s_cmp_lg_u32 s40, 1
	v_lshl_add_u64 v[2:3], s[44:45], 0, v[128:129]
	s_cbranch_scc1 .LBB0_692
	s_barrier
.LBB0_692:
	s_add_u32 s8, s8, 0x35000000
	v_lshrrev_b32_e32 v12, 1, v10
	s_addc_u32 s9, s9, 0
	v_and_b32_e32 v11, 15, v10
	v_and_b32_e32 v12, 24, v12
	s_lshl_b32 s11, s11, 5
	v_lshl_or_b32 v142, s40, 6, v11
	v_lshlrev_b32_e32 v13, 1, v12
	s_lshl_b32 s38, s40, 13
	v_lshlrev_b32_e32 v10, 2, v10
	s_and_b32 s40, s11, 0x60
	s_add_i32 m0, s36, 0x18000
	v_lshl_add_u64 v[0:1], v[0:1], 0, s[26:27]
	v_lshl_or_b32 v11, v11, 6, v13
	v_and_b32_e32 v10, 32, v10
	s_lshl_b32 s11, s40, 7
	s_waitcnt vmcnt(2)
	s_barrier
	global_load_lds_dwordx4 v[0:1], off
	s_add_i32 m0, s36, 0x1a000
	v_bitop3_b32 v13, v11, s38, v10 bitop3:0xde
	s_add_u32 s38, s44, 0x200080
	v_lshl_add_u64 v[0:1], v[2:3], 0, s[26:27]
	s_addc_u32 s39, s45, 0
	global_load_lds_dwordx4 v[0:1], off
	s_add_i32 m0, s36, 0x1c000
	v_lshl_add_u64 v[0:1], s[38:39], 0, v[204:205]
	global_load_lds_dwordx4 v[0:1], off
	v_lshl_add_u64 v[0:1], s[38:39], 0, v[128:129]
	s_add_i32 m0, s36, 0x1e000
	s_cmpk_lt_u32 s10, 0x100
	global_load_lds_dwordx4 v[0:1], off
	v_lshlrev_b32_e32 v0, 17, v8
	v_and_b32_e32 v0, 0xfffc0000, v0
	v_lshl_add_u32 v0, v7, 14, v0
	v_and_b32_e32 v1, 1, v8
	v_lshl_or_b32 v0, v1, 6, v0
	v_lshl_add_u32 v134, v9, 1, v0
	v_lshlrev_b32_e32 v0, 17, v4
	v_and_b32_e32 v0, 0xfffc0000, v0
	s_waitcnt vmcnt(4)
	v_lshl_add_u32 v0, v5, 14, v0
	v_and_b32_e32 v1, 1, v4
	v_lshl_or_b32 v0, v1, 6, v0
	v_readlane_b32 s38, v255, 20
	v_mov_b32_e32 v133, v205
	v_mov_b32_e32 v131, v205
	v_bitop3_b32 v143, v11, s11, v10 bitop3:0xde
	s_cselect_b64 s[10:11], -1, 0
	v_or_b32_e32 v144, s40, v12
	v_mov_b32_e32 v135, v205
	v_lshl_add_u32 v136, v6, 1, v0
	v_mov_b32_e32 v137, v205
	s_mov_b32 s84, 0
	v_add_u32_e32 v145, 0, v13
	v_readlane_b32 s95, v254, 60
	s_nop 3
	s_bfe_u32 s32, s38, 0x10002
	s_lshl_b32 s95, s95, 1
	s_add_i32 s95, s95, s32
	s_bitset0_b32 s38, 2
	s_mov_b32 s94, s38
	s_barrier
	v_readlane_b32 s39, v255, 21
	s_branch .LBB0_695

;     __host__ __device__ bool next(int i, Unit& u) const {
;         const long L = (long)i * G + c; if (L >= nwg) return false;
;         int wgid = (int)L; { const int q = nwg / NXCD, r = nwg % NXCD, xcd = wgid % NXCD, off = wgid / NXCD; wgid = (xcd < r ? xcd * (q + 1) : r * (q + 1) + (xcd - r) * q) + off; }
;         const int nig = WGM * nN, gid = wgid / nig, fm = gid * WGM, gsz = (nM - fm) < WGM ? (nM - fm) : WGM;
;         u.pm = fm + ((wgid % nig) % gsz); u.pn = (wgid % nig) / gsz; return true;
.LBB0_700:
	s_ashr_i32 s38, s46, 3
	s_add_i32 s38, s52, s38
	s_ashr_i32 s39, s38, 31
	s_lshr_b32 s39, s39, 26
	s_add_i32 s39, s38, s39
	s_ashr_i32 s42, s39, 6
	s_lshl_b32 s43, s42, 3
	s_sub_i32 s42, 64, s43
	s_min_i32 s46, s42, 8
	s_abs_i32 s42, s46
	v_cvt_f32_u32_e32 v0, s42
	s_sub_i32 s52, 0, s42
	s_andn2_b32 s39, s39, 63
	s_sub_i32 s38, s38, s39
	v_rcp_iflag_f32_e32 v0, v0
	s_abs_i32 s39, s38
	s_xor_b32 s47, s38, s46
	s_ashr_i32 s47, s47, 31
	v_mul_f32_e32 v0, 0x4f7ffffe, v0
	v_cvt_u32_f32_e32 v0, v0
	s_nop 0
	v_readfirstlane_b32 s53, v0
	s_mul_i32 s52, s52, s53
	s_mul_hi_u32 s52, s53, s52
	s_add_i32 s53, s53, s52
	s_mul_hi_u32 s52, s39, s53
	s_mul_i32 s53, s52, s42
	s_sub_i32 s39, s39, s53
	s_add_i32 s68, s52, 1
	s_sub_i32 s53, s39, s42
	s_cmp_ge_u32 s39, s42
	s_cselect_b32 s52, s68, s52
	s_cselect_b32 s39, s53, s39
	s_add_i32 s53, s52, 1
	s_cmp_ge_u32 s39, s42
	s_cselect_b32 s39, s53, s52
	s_xor_b32 s39, s39, s47
	s_sub_i32 s42, s39, s47
	s_mul_i32 s39, s42, s46
	s_sub_i32 s38, s38, s39
	s_add_i32 s46, s43, s38
	s_and_b32 s38, s46, 7
	s_and_b32 s39, s46, -8
	s_lshr_b32 s43, s42, 2
	s_lshl_b32 s43, s43, 2
	s_add_i32 s39, s39, s43
	s_and_b32 s43, s38, 3
	s_add_i32 s46, s39, s43
	s_and_b32 s43, s42, 3
	s_lshl_b32 s43, s43, 1
	s_lshr_b32 s38, s38, 2
	s_add_i32 s42, s43, s38
